# resid phases: residual-row (Pre) loads issued in a peeled last K iteration after its A11 pieces, that iteration's vmcnt waits recounted (22/18, next-tile waits skipped when no next tile), drained befo
# baseline (speedup 1.0000x reference)
.Lrs_first_tile:
	s_waitcnt vmcnt(6)
	v_add_u32_e32 v96, 0x10000, v225
	ds_read_b128 v[80:83], v96 offset:2048
	ds_read_b128 v[98:101], v96 offset:3072
	s_add_i32 vcc_hi, s46, 2
	s_add_u32 s84, s44, 0x80
	s_addc_u32 s47, s45, 0
	s_add_i32 s29, 0, 0x10000
	v_add_u32_e32 v96, s29, v225
	ds_read_b128 v[56:59], v96
	ds_read_b128 v[68:71], v96 offset:1024
	s_cmp_eq_u32 s90, s46
	s_cselect_b32 s46, s80, s84
	s_cselect_b32 s47, s81, s47
	s_cselect_b32 s85, s83, vcc_lo
	s_cselect_b32 s84, s82, s87
	s_add_i32 m0, s2, 0xc000
	ds_read_b128 v[102:105], v227
	ds_read_b128 v[112:115], v227 offset:1024
	ds_read_b128 v[124:127], v227 offset:2048
	ds_read_b128 v[192:195], v227 offset:3072
	ds_read_b128 v[196:199], v227 offset:4096
	ds_read_b128 v[200:203], v227 offset:5120
	global_load_lds_dwordx4 v188, s[44:45]
	s_add_i32 m0, s2, 0xe000
	s_mov_b64 exec, s[98:99]
	global_load_lds_dwordx4 v190, s[44:45]
	s_mov_b64 exec, -1
	s_waitcnt lgkmcnt(6)
	s_setprio 1
	s_barrier
	s_waitcnt lgkmcnt(0)
	v_mfma_f32_16x16x32_bf16 v[172:175], v[56:59], v[102:105], 0
	v_mfma_f32_16x16x32_bf16 v[168:171], v[80:83], v[102:105], 0
	v_mfma_f32_16x16x32_bf16 v[156:159], v[56:59], v[124:127], 0
	v_mfma_f32_16x16x32_bf16 v[152:155], v[80:83], v[124:127], 0
	v_mfma_f32_16x16x32_bf16 v[132:135], v[56:59], v[196:199], 0
	v_mfma_f32_16x16x32_bf16 v[128:131], v[80:83], v[196:199], 0
	v_mfma_f32_16x16x32_bf16 v[172:175], v[68:71], v[112:115], v[172:175]
	v_mfma_f32_16x16x32_bf16 v[168:171], v[98:101], v[112:115], v[168:171]
	v_mfma_f32_16x16x32_bf16 v[156:159], v[68:71], v[192:195], v[156:159]
	v_mfma_f32_16x16x32_bf16 v[152:155], v[98:101], v[192:195], v[152:155]
	v_mfma_f32_16x16x32_bf16 v[132:135], v[68:71], v[200:203], v[132:135]
	v_mfma_f32_16x16x32_bf16 v[128:131], v[98:101], v[200:203], v[128:131]
	s_barrier
	s_setprio 0
	s_add_i32 s96, 0, 0x14000
	s_add_i32 s29, s29, s18
	v_add_u32_e32 v96, s96, v225
	v_lshl_add_u64 v[106:107], s[84:85], 0, v[182:183]
	s_mov_b32 m0, s29
	ds_read_b128 v[228:231], v96
	ds_read_b128 v[232:235], v96 offset:1024
	ds_read_b128 v[236:239], v96 offset:2048
	ds_read_b128 v[240:243], v96 offset:3072
	global_load_lds_dwordx4 v182, s[84:85]
	v_lshl_add_u64 v[248:249], s[84:85], 0, v[186:187]
	s_add_i32 m0, s29, 0x2000
	s_nop 0
	global_load_lds_dwordx4 v186, s[84:85]
	s_setprio 1
	s_barrier
	s_waitcnt lgkmcnt(0)
	v_mfma_f32_16x16x32_bf16 v[164:167], v[228:231], v[102:105], 0
	v_mfma_f32_16x16x32_bf16 v[102:105], v[236:239], v[102:105], 0
	v_mfma_f32_16x16x32_bf16 v[120:123], v[228:231], v[196:199], 0
	s_mov_b32 m0, s2
	v_mfma_f32_16x16x32_bf16 v[116:119], v[236:239], v[196:199], 0
	v_lshl_add_u64 v[250:251], s[46:47], 0, v[176:177]
	v_mfma_f32_16x16x32_bf16 v[164:167], v[232:235], v[112:115], v[164:167]
	v_mfma_f32_16x16x32_bf16 v[102:105], v[240:243], v[112:115], v[102:105]
	v_mfma_f32_16x16x32_bf16 v[112:115], v[228:231], v[124:127], 0
	v_mfma_f32_16x16x32_bf16 v[124:127], v[236:239], v[124:127], 0
	v_mfma_f32_16x16x32_bf16 v[120:123], v[232:235], v[200:203], v[120:123]
	v_mfma_f32_16x16x32_bf16 v[116:119], v[240:243], v[200:203], v[116:119]
	v_mfma_f32_16x16x32_bf16 v[112:115], v[232:235], v[192:195], v[112:115]
	v_mfma_f32_16x16x32_bf16 v[124:127], v[240:243], v[192:195], v[124:127]
	s_barrier
	s_setprio 0
	ds_read_b128 v[144:147], v227 offset:16384
	ds_read_b128 v[148:151], v227 offset:17408
	ds_read_b128 v[160:163], v227 offset:18432
	ds_read_b128 v[192:195], v227 offset:19456
	ds_read_b128 v[196:199], v227 offset:20480
	ds_read_b128 v[200:203], v227 offset:21504
	global_load_lds_dwordx4 v176, s[46:47]
	v_lshl_add_u64 v[252:253], s[46:47], 0, v[184:185]
	s_mov_b32 m0, s3
	s_mov_b64 exec, s[98:99]
	global_load_lds_dwordx4 v184, s[46:47]
	s_mov_b64 exec, -1
	s_waitcnt vmcnt(10)
	s_setprio 1
	s_barrier
	s_waitcnt lgkmcnt(0)
	v_mfma_f32_16x16x32_bf16 v[88:91], v[56:59], v[144:147], 0
	v_mfma_f32_16x16x32_bf16 v[84:87], v[80:83], v[144:147], 0
	v_mfma_f32_16x16x32_bf16 v[52:55], v[56:59], v[160:163], 0
	v_mfma_f32_16x16x32_bf16 v[48:51], v[80:83], v[160:163], 0
	v_mfma_f32_16x16x32_bf16 v[28:31], v[56:59], v[196:199], 0
	v_mfma_f32_16x16x32_bf16 v[24:27], v[80:83], v[196:199], 0
	v_mfma_f32_16x16x32_bf16 v[88:91], v[68:71], v[148:151], v[88:91]
	v_mfma_f32_16x16x32_bf16 v[84:87], v[98:101], v[148:151], v[84:87]
	v_mfma_f32_16x16x32_bf16 v[52:55], v[68:71], v[192:195], v[52:55]
	v_mfma_f32_16x16x32_bf16 v[48:51], v[98:101], v[192:195], v[48:51]
	v_mfma_f32_16x16x32_bf16 v[28:31], v[68:71], v[200:203], v[28:31]
	v_mfma_f32_16x16x32_bf16 v[24:27], v[98:101], v[200:203], v[24:27]
	s_barrier
	s_setprio 0
	v_add_u32_e32 v96, 0x18000, v225
	ds_read_b128 v[80:83], v96 offset:2048
	ds_read_b128 v[98:101], v96 offset:3072
	s_add_u32 s84, s84, s57
	s_addc_u32 s85, s85, 0
	s_add_i32 s29, s96, s18
	v_lshl_add_u64 v[218:219], s[84:85], 0, v[182:183]
	s_mov_b32 m0, s29
	v_lshl_add_u64 v[220:221], s[84:85], 0, v[186:187]
	global_load_lds_dwordx4 v182, s[84:85]
	s_add_i32 m0, s29, 0x2000
	s_nop 0
	global_load_lds_dwordx4 v186, s[84:85]
	s_waitcnt vmcnt(6)
	s_setprio 1
	s_barrier
	v_mfma_f32_16x16x32_bf16 v[44:47], v[228:231], v[160:163], 0
	v_mfma_f32_16x16x32_bf16 v[40:43], v[236:239], v[160:163], 0
	v_mfma_f32_16x16x32_bf16 v[20:23], v[228:231], v[196:199], 0
	s_add_i32 s29, 0, 0x18000
	v_mfma_f32_16x16x32_bf16 v[16:19], v[236:239], v[196:199], 0
	v_add_u32_e32 v96, s29, v225
	v_mfma_f32_16x16x32_bf16 v[56:59], v[228:231], v[144:147], 0
	v_mfma_f32_16x16x32_bf16 v[68:71], v[236:239], v[144:147], 0
	v_mfma_f32_16x16x32_bf16 v[44:47], v[232:235], v[192:195], v[44:47]
	v_mfma_f32_16x16x32_bf16 v[40:43], v[240:243], v[192:195], v[40:43]
	v_mfma_f32_16x16x32_bf16 v[20:23], v[232:235], v[200:203], v[20:23]
	v_mfma_f32_16x16x32_bf16 v[16:19], v[240:243], v[200:203], v[16:19]
	v_mfma_f32_16x16x32_bf16 v[56:59], v[232:235], v[148:151], v[56:59]
	v_mfma_f32_16x16x32_bf16 v[68:71], v[240:243], v[148:151], v[68:71]
	s_barrier
	s_setprio 0
	ds_read_b128 v[72:75], v96
	ds_read_b128 v[76:79], v96 offset:1024
	s_add_u32 s46, s46, s64
	s_addc_u32 s47, s47, 0
	s_mov_b32 m0, s4
	ds_read_b128 v[144:147], v227 offset:32768
	ds_read_b128 v[148:151], v227 offset:33792
	ds_read_b128 v[192:195], v227 offset:34816
	ds_read_b128 v[196:199], v227 offset:35840
	ds_read_b128 v[200:203], v227 offset:36864
	ds_read_b128 v[228:231], v227 offset:37888
	global_load_lds_dwordx4 v176, s[46:47]
	s_mov_b32 m0, s5
	s_mov_b64 exec, s[98:99]
	global_load_lds_dwordx4 v184, s[46:47]
	s_mov_b64 exec, -1
	s_waitcnt lgkmcnt(6)
	s_setprio 1
	s_barrier
	s_waitcnt lgkmcnt(0)
	v_mfma_f32_16x16x32_bf16 v[160:163], v[72:75], v[144:147], v[172:175]
	v_mfma_f32_16x16x32_bf16 v[172:175], v[76:79], v[148:151], v[160:163]
	v_mfma_f32_16x16x32_bf16 v[160:163], v[80:83], v[144:147], v[168:171]
	v_mfma_f32_16x16x32_bf16 v[156:159], v[72:75], v[192:195], v[156:159]
	v_mfma_f32_16x16x32_bf16 v[152:155], v[80:83], v[192:195], v[152:155]
	v_mfma_f32_16x16x32_bf16 v[132:135], v[72:75], v[200:203], v[132:135]
	v_mfma_f32_16x16x32_bf16 v[128:131], v[80:83], v[200:203], v[128:131]
	v_mfma_f32_16x16x32_bf16 v[168:171], v[98:101], v[148:151], v[160:163]
	v_mfma_f32_16x16x32_bf16 v[156:159], v[76:79], v[196:199], v[156:159]
	v_mfma_f32_16x16x32_bf16 v[152:155], v[98:101], v[196:199], v[152:155]
	v_mfma_f32_16x16x32_bf16 v[132:135], v[76:79], v[228:231], v[132:135]
	v_mfma_f32_16x16x32_bf16 v[128:131], v[98:101], v[228:231], v[128:131]
	s_barrier
	s_setprio 0
	s_add_i32 s46, 0, 0x1c000
	s_add_i32 s29, s29, s18
	v_add_u32_e32 v96, s46, v225
	v_lshl_add_u64 v[106:107], v[106:107], 0, s[6:7]
	s_mov_b32 m0, s29
	ds_read_b128 v[232:235], v96
	ds_read_b128 v[236:239], v96 offset:1024
	ds_read_b128 v[240:243], v96 offset:2048
	ds_read_b128 v[244:247], v96 offset:3072
	global_load_lds_dwordx4 v[106:107], off
	v_lshl_add_u64 v[106:107], v[248:249], 0, s[6:7]
	s_add_i32 m0, s29, 0x2000
	s_nop 0
	global_load_lds_dwordx4 v[106:107], off
	s_setprio 1
	s_barrier
	s_waitcnt lgkmcnt(0)
	v_mfma_f32_16x16x32_bf16 v[160:163], v[232:235], v[144:147], v[164:167]
	v_mfma_f32_16x16x32_bf16 v[102:105], v[240:243], v[144:147], v[102:105]
	v_mfma_f32_16x16x32_bf16 v[164:167], v[236:239], v[148:151], v[160:163]
	s_mov_b32 m0, s88
	v_mfma_f32_16x16x32_bf16 v[160:163], v[244:247], v[148:151], v[102:105]
	v_lshl_add_u64 v[106:107], v[250:251], 0, s[6:7]
	v_mfma_f32_16x16x32_bf16 v[102:105], v[232:235], v[192:195], v[112:115]
	v_mfma_f32_16x16x32_bf16 v[148:151], v[236:239], v[196:199], v[102:105]
	v_mfma_f32_16x16x32_bf16 v[102:105], v[240:243], v[192:195], v[124:127]
	v_mfma_f32_16x16x32_bf16 v[144:147], v[244:247], v[196:199], v[102:105]
	v_mfma_f32_16x16x32_bf16 v[102:105], v[232:235], v[200:203], v[120:123]
	v_mfma_f32_16x16x32_bf16 v[120:123], v[236:239], v[228:231], v[102:105]
	v_mfma_f32_16x16x32_bf16 v[102:105], v[240:243], v[200:203], v[116:119]
	v_mfma_f32_16x16x32_bf16 v[116:119], v[244:247], v[228:231], v[102:105]
	s_barrier
	s_setprio 0
	s_nop 2
	ds_read_b128 v[102:105], v227 offset:49152
	ds_read_b128 v[112:115], v227 offset:50176
	ds_read_b128 v[124:127], v227 offset:51200
	ds_read_b128 v[192:195], v227 offset:52224
	ds_read_b128 v[196:199], v227 offset:53248
	ds_read_b128 v[200:203], v227 offset:54272
	global_load_lds_dwordx4 v[106:107], off
	v_lshl_add_u64 v[106:107], v[252:253], 0, s[6:7]
	s_mov_b32 m0, s89
	s_mov_b64 exec, s[98:99]
	global_load_lds_dwordx4 v[106:107], off
	s_mov_b64 exec, -1
	s_waitcnt vmcnt(10)
	s_setprio 1
	s_barrier
	s_waitcnt lgkmcnt(0)
	v_mfma_f32_16x16x32_bf16 v[88:91], v[72:75], v[102:105], v[88:91]
	v_mfma_f32_16x16x32_bf16 v[84:87], v[80:83], v[102:105], v[84:87]
	v_mfma_f32_16x16x32_bf16 v[52:55], v[72:75], v[124:127], v[52:55]
	v_mfma_f32_16x16x32_bf16 v[48:51], v[80:83], v[124:127], v[48:51]
	v_mfma_f32_16x16x32_bf16 v[28:31], v[72:75], v[196:199], v[28:31]
	v_mfma_f32_16x16x32_bf16 v[24:27], v[80:83], v[196:199], v[24:27]
	v_mfma_f32_16x16x32_bf16 v[88:91], v[76:79], v[112:115], v[88:91]
	v_mfma_f32_16x16x32_bf16 v[84:87], v[98:101], v[112:115], v[84:87]
	v_mfma_f32_16x16x32_bf16 v[52:55], v[76:79], v[192:195], v[52:55]
	v_mfma_f32_16x16x32_bf16 v[48:51], v[98:101], v[192:195], v[48:51]
	v_mfma_f32_16x16x32_bf16 v[28:31], v[76:79], v[200:203], v[28:31]
	v_mfma_f32_16x16x32_bf16 v[24:27], v[98:101], v[200:203], v[24:27]
	s_barrier
	s_setprio 0
	v_add_u32_e32 v96, 0x10000, v225
	ds_read_b128 v[80:83], v96 offset:2048
	ds_read_b128 v[98:101], v96 offset:3072
	s_add_i32 s29, s46, s18
	v_lshl_add_u64 v[72:73], v[218:219], 0, s[6:7]
	s_mov_b32 m0, s29
	s_nop 0
	global_load_lds_dwordx4 v[72:73], off
	v_lshl_add_u64 v[72:73], v[220:221], 0, s[6:7]
	s_add_i32 m0, s29, 0x2000
	s_nop 0
	global_load_lds_dwordx4 v[72:73], off
	s_waitcnt vmcnt(6)
	s_setprio 1
	s_barrier
	v_mfma_f32_16x16x32_bf16 v[56:59], v[232:235], v[102:105], v[56:59]
	v_mfma_f32_16x16x32_bf16 v[76:79], v[236:239], v[112:115], v[56:59]
	v_mfma_f32_16x16x32_bf16 v[56:59], v[240:243], v[102:105], v[68:71]
	s_add_u32 s44, s44, 0x100
	v_mfma_f32_16x16x32_bf16 v[44:47], v[232:235], v[124:127], v[44:47]
	s_addc_u32 s45, s45, 0
	v_mfma_f32_16x16x32_bf16 v[40:43], v[240:243], v[124:127], v[40:43]
	s_add_u32 s87, s87, 0x100
	v_mfma_f32_16x16x32_bf16 v[20:23], v[232:235], v[196:199], v[20:23]
	s_addc_u32 vcc_lo, vcc_lo, 0
	v_mfma_f32_16x16x32_bf16 v[16:19], v[240:243], v[196:199], v[16:19]
	s_add_i32 s100, vcc_hi, 2
	s_cmp_ge_u32 s100, s37
	v_mfma_f32_16x16x32_bf16 v[72:75], v[244:247], v[112:115], v[56:59]
	s_mov_b32 s46, vcc_hi
	v_mfma_f32_16x16x32_bf16 v[44:47], v[236:239], v[192:195], v[44:47]
	v_mfma_f32_16x16x32_bf16 v[40:43], v[244:247], v[192:195], v[40:43]
	v_mfma_f32_16x16x32_bf16 v[20:23], v[236:239], v[200:203], v[20:23]
	v_mfma_f32_16x16x32_bf16 v[16:19], v[244:247], v[200:203], v[16:19]
	s_barrier
	s_setprio 0
	s_cbranch_scc1 .Lrs_last
.LBB0_1021:
	s_add_i32 vcc_hi, s46, 2
	s_add_u32 s84, s44, 0x80
	s_addc_u32 s47, s45, 0
	s_add_i32 s29, 0, 0x10000
	v_add_u32_e32 v96, s29, v225
	ds_read_b128 v[56:59], v96
	ds_read_b128 v[68:71], v96 offset:1024
	s_cmp_eq_u32 s90, s46
	s_cselect_b32 s46, s80, s84
	s_cselect_b32 s47, s81, s47
	s_cselect_b32 s85, s83, vcc_lo
	s_cselect_b32 s84, s82, s87
	s_add_i32 m0, s2, 0xc000
	ds_read_b128 v[102:105], v227
	ds_read_b128 v[112:115], v227 offset:1024
	ds_read_b128 v[124:127], v227 offset:2048
	ds_read_b128 v[192:195], v227 offset:3072
	ds_read_b128 v[196:199], v227 offset:4096
	ds_read_b128 v[200:203], v227 offset:5120
	global_load_lds_dwordx4 v188, s[44:45]
	s_add_i32 m0, s2, 0xe000
	s_mov_b64 exec, s[98:99]
	global_load_lds_dwordx4 v190, s[44:45]
	s_mov_b64 exec, -1
	s_waitcnt lgkmcnt(6)
	s_setprio 1
	s_barrier
	s_waitcnt lgkmcnt(0)
	v_mfma_f32_16x16x32_bf16 v[172:175], v[56:59], v[102:105], v[172:175]
	v_mfma_f32_16x16x32_bf16 v[168:171], v[80:83], v[102:105], v[168:171]
	v_mfma_f32_16x16x32_bf16 v[156:159], v[56:59], v[124:127], v[156:159]
	v_mfma_f32_16x16x32_bf16 v[152:155], v[80:83], v[124:127], v[152:155]
	v_mfma_f32_16x16x32_bf16 v[132:135], v[56:59], v[196:199], v[132:135]
	v_mfma_f32_16x16x32_bf16 v[128:131], v[80:83], v[196:199], v[128:131]
	v_mfma_f32_16x16x32_bf16 v[172:175], v[68:71], v[112:115], v[172:175]
	v_mfma_f32_16x16x32_bf16 v[168:171], v[98:101], v[112:115], v[168:171]
	v_mfma_f32_16x16x32_bf16 v[156:159], v[68:71], v[192:195], v[156:159]
	v_mfma_f32_16x16x32_bf16 v[152:155], v[98:101], v[192:195], v[152:155]
	v_mfma_f32_16x16x32_bf16 v[132:135], v[68:71], v[200:203], v[132:135]
	v_mfma_f32_16x16x32_bf16 v[128:131], v[98:101], v[200:203], v[128:131]
	s_barrier
	s_setprio 0
	s_add_i32 s96, 0, 0x14000
	s_add_i32 s29, s29, s18
	v_add_u32_e32 v96, s96, v225
	v_lshl_add_u64 v[106:107], s[84:85], 0, v[182:183]
	s_mov_b32 m0, s29
	ds_read_b128 v[228:231], v96
	ds_read_b128 v[232:235], v96 offset:1024
	ds_read_b128 v[236:239], v96 offset:2048
	ds_read_b128 v[240:243], v96 offset:3072
	global_load_lds_dwordx4 v182, s[84:85]
	v_lshl_add_u64 v[248:249], s[84:85], 0, v[186:187]
	s_add_i32 m0, s29, 0x2000
	s_nop 0
	global_load_lds_dwordx4 v186, s[84:85]
	s_setprio 1
	s_barrier
	s_waitcnt lgkmcnt(0)
	v_mfma_f32_16x16x32_bf16 v[164:167], v[228:231], v[102:105], v[164:167]
	v_mfma_f32_16x16x32_bf16 v[102:105], v[236:239], v[102:105], v[160:163]
	v_mfma_f32_16x16x32_bf16 v[120:123], v[228:231], v[196:199], v[120:123]
	s_mov_b32 m0, s2
	v_mfma_f32_16x16x32_bf16 v[116:119], v[236:239], v[196:199], v[116:119]
	v_lshl_add_u64 v[250:251], s[46:47], 0, v[176:177]
	v_mfma_f32_16x16x32_bf16 v[164:167], v[232:235], v[112:115], v[164:167]
	v_mfma_f32_16x16x32_bf16 v[102:105], v[240:243], v[112:115], v[102:105]
	v_mfma_f32_16x16x32_bf16 v[112:115], v[228:231], v[124:127], v[148:151]
	v_mfma_f32_16x16x32_bf16 v[124:127], v[236:239], v[124:127], v[144:147]
	v_mfma_f32_16x16x32_bf16 v[120:123], v[232:235], v[200:203], v[120:123]
	v_mfma_f32_16x16x32_bf16 v[116:119], v[240:243], v[200:203], v[116:119]
	v_mfma_f32_16x16x32_bf16 v[112:115], v[232:235], v[192:195], v[112:115]
	v_mfma_f32_16x16x32_bf16 v[124:127], v[240:243], v[192:195], v[124:127]
	s_barrier
	s_setprio 0
	ds_read_b128 v[144:147], v227 offset:16384
	ds_read_b128 v[148:151], v227 offset:17408
	ds_read_b128 v[160:163], v227 offset:18432
	ds_read_b128 v[192:195], v227 offset:19456
	ds_read_b128 v[196:199], v227 offset:20480
	ds_read_b128 v[200:203], v227 offset:21504
	global_load_lds_dwordx4 v176, s[46:47]
	v_lshl_add_u64 v[252:253], s[46:47], 0, v[184:185]
	s_mov_b32 m0, s3
	s_mov_b64 exec, s[98:99]
	global_load_lds_dwordx4 v184, s[46:47]
	s_mov_b64 exec, -1
	s_waitcnt vmcnt(10)
	s_setprio 1
	s_barrier
	s_waitcnt lgkmcnt(0)
	v_mfma_f32_16x16x32_bf16 v[88:91], v[56:59], v[144:147], v[88:91]
	v_mfma_f32_16x16x32_bf16 v[84:87], v[80:83], v[144:147], v[84:87]
	v_mfma_f32_16x16x32_bf16 v[52:55], v[56:59], v[160:163], v[52:55]
	v_mfma_f32_16x16x32_bf16 v[48:51], v[80:83], v[160:163], v[48:51]
	v_mfma_f32_16x16x32_bf16 v[28:31], v[56:59], v[196:199], v[28:31]
	v_mfma_f32_16x16x32_bf16 v[24:27], v[80:83], v[196:199], v[24:27]
	v_mfma_f32_16x16x32_bf16 v[88:91], v[68:71], v[148:151], v[88:91]
	v_mfma_f32_16x16x32_bf16 v[84:87], v[98:101], v[148:151], v[84:87]
	v_mfma_f32_16x16x32_bf16 v[52:55], v[68:71], v[192:195], v[52:55]
	v_mfma_f32_16x16x32_bf16 v[48:51], v[98:101], v[192:195], v[48:51]
	v_mfma_f32_16x16x32_bf16 v[28:31], v[68:71], v[200:203], v[28:31]
	v_mfma_f32_16x16x32_bf16 v[24:27], v[98:101], v[200:203], v[24:27]
	s_barrier
	s_setprio 0
	v_add_u32_e32 v96, 0x18000, v225
	ds_read_b128 v[80:83], v96 offset:2048
	ds_read_b128 v[98:101], v96 offset:3072
	s_add_u32 s84, s84, s57
	s_addc_u32 s85, s85, 0
	s_add_i32 s29, s96, s18
	v_lshl_add_u64 v[218:219], s[84:85], 0, v[182:183]
	s_mov_b32 m0, s29
	v_lshl_add_u64 v[220:221], s[84:85], 0, v[186:187]
	global_load_lds_dwordx4 v182, s[84:85]
	s_add_i32 m0, s29, 0x2000
	s_nop 0
	global_load_lds_dwordx4 v186, s[84:85]
	s_waitcnt vmcnt(6)
	s_setprio 1
	s_barrier
	v_mfma_f32_16x16x32_bf16 v[44:47], v[228:231], v[160:163], v[44:47]
	v_mfma_f32_16x16x32_bf16 v[40:43], v[236:239], v[160:163], v[40:43]
	v_mfma_f32_16x16x32_bf16 v[20:23], v[228:231], v[196:199], v[20:23]
	s_add_i32 s29, 0, 0x18000
	v_mfma_f32_16x16x32_bf16 v[16:19], v[236:239], v[196:199], v[16:19]
	v_add_u32_e32 v96, s29, v225
	v_mfma_f32_16x16x32_bf16 v[56:59], v[228:231], v[144:147], v[76:79]
	v_mfma_f32_16x16x32_bf16 v[68:71], v[236:239], v[144:147], v[72:75]
	v_mfma_f32_16x16x32_bf16 v[44:47], v[232:235], v[192:195], v[44:47]
	v_mfma_f32_16x16x32_bf16 v[40:43], v[240:243], v[192:195], v[40:43]
	v_mfma_f32_16x16x32_bf16 v[20:23], v[232:235], v[200:203], v[20:23]
	v_mfma_f32_16x16x32_bf16 v[16:19], v[240:243], v[200:203], v[16:19]
	v_mfma_f32_16x16x32_bf16 v[56:59], v[232:235], v[148:151], v[56:59]
	v_mfma_f32_16x16x32_bf16 v[68:71], v[240:243], v[148:151], v[68:71]
	s_barrier
	s_setprio 0
	ds_read_b128 v[72:75], v96
	ds_read_b128 v[76:79], v96 offset:1024
	s_add_u32 s46, s46, s64
	s_addc_u32 s47, s47, 0
	s_mov_b32 m0, s4
	ds_read_b128 v[144:147], v227 offset:32768
	ds_read_b128 v[148:151], v227 offset:33792
	ds_read_b128 v[192:195], v227 offset:34816
	ds_read_b128 v[196:199], v227 offset:35840
	ds_read_b128 v[200:203], v227 offset:36864
	ds_read_b128 v[228:231], v227 offset:37888
	global_load_lds_dwordx4 v176, s[46:47]
	s_mov_b32 m0, s5
	s_mov_b64 exec, s[98:99]
	global_load_lds_dwordx4 v184, s[46:47]
	s_mov_b64 exec, -1
	s_waitcnt lgkmcnt(6)
	s_setprio 1
	s_barrier
	s_waitcnt lgkmcnt(0)
	v_mfma_f32_16x16x32_bf16 v[160:163], v[72:75], v[144:147], v[172:175]
	v_mfma_f32_16x16x32_bf16 v[172:175], v[76:79], v[148:151], v[160:163]
	v_mfma_f32_16x16x32_bf16 v[160:163], v[80:83], v[144:147], v[168:171]
	v_mfma_f32_16x16x32_bf16 v[156:159], v[72:75], v[192:195], v[156:159]
	v_mfma_f32_16x16x32_bf16 v[152:155], v[80:83], v[192:195], v[152:155]
	v_mfma_f32_16x16x32_bf16 v[132:135], v[72:75], v[200:203], v[132:135]
	v_mfma_f32_16x16x32_bf16 v[128:131], v[80:83], v[200:203], v[128:131]
	v_mfma_f32_16x16x32_bf16 v[168:171], v[98:101], v[148:151], v[160:163]
	v_mfma_f32_16x16x32_bf16 v[156:159], v[76:79], v[196:199], v[156:159]
	v_mfma_f32_16x16x32_bf16 v[152:155], v[98:101], v[196:199], v[152:155]
	v_mfma_f32_16x16x32_bf16 v[132:135], v[76:79], v[228:231], v[132:135]
	v_mfma_f32_16x16x32_bf16 v[128:131], v[98:101], v[228:231], v[128:131]
	s_barrier
	s_setprio 0
	s_add_i32 s46, 0, 0x1c000
	s_add_i32 s29, s29, s18
	v_add_u32_e32 v96, s46, v225
	v_lshl_add_u64 v[106:107], v[106:107], 0, s[6:7]
	s_mov_b32 m0, s29
	ds_read_b128 v[232:235], v96
	ds_read_b128 v[236:239], v96 offset:1024
	ds_read_b128 v[240:243], v96 offset:2048
	ds_read_b128 v[244:247], v96 offset:3072
	global_load_lds_dwordx4 v[106:107], off
	v_lshl_add_u64 v[106:107], v[248:249], 0, s[6:7]
	s_add_i32 m0, s29, 0x2000
	s_nop 0
	global_load_lds_dwordx4 v[106:107], off
	s_setprio 1
	s_barrier
	s_waitcnt lgkmcnt(0)
	v_mfma_f32_16x16x32_bf16 v[160:163], v[232:235], v[144:147], v[164:167]
	v_mfma_f32_16x16x32_bf16 v[102:105], v[240:243], v[144:147], v[102:105]
	v_mfma_f32_16x16x32_bf16 v[164:167], v[236:239], v[148:151], v[160:163]
	s_mov_b32 m0, s88
	v_mfma_f32_16x16x32_bf16 v[160:163], v[244:247], v[148:151], v[102:105]
	v_lshl_add_u64 v[106:107], v[250:251], 0, s[6:7]
	v_mfma_f32_16x16x32_bf16 v[102:105], v[232:235], v[192:195], v[112:115]
	v_mfma_f32_16x16x32_bf16 v[148:151], v[236:239], v[196:199], v[102:105]
	v_mfma_f32_16x16x32_bf16 v[102:105], v[240:243], v[192:195], v[124:127]
	v_mfma_f32_16x16x32_bf16 v[144:147], v[244:247], v[196:199], v[102:105]
	v_mfma_f32_16x16x32_bf16 v[102:105], v[232:235], v[200:203], v[120:123]
	v_mfma_f32_16x16x32_bf16 v[120:123], v[236:239], v[228:231], v[102:105]
	v_mfma_f32_16x16x32_bf16 v[102:105], v[240:243], v[200:203], v[116:119]
	v_mfma_f32_16x16x32_bf16 v[116:119], v[244:247], v[228:231], v[102:105]
	s_barrier
	s_setprio 0
	s_nop 2
	ds_read_b128 v[102:105], v227 offset:49152
	ds_read_b128 v[112:115], v227 offset:50176
	ds_read_b128 v[124:127], v227 offset:51200
	ds_read_b128 v[192:195], v227 offset:52224
	ds_read_b128 v[196:199], v227 offset:53248
	ds_read_b128 v[200:203], v227 offset:54272
	global_load_lds_dwordx4 v[106:107], off
	v_lshl_add_u64 v[106:107], v[252:253], 0, s[6:7]
	s_mov_b32 m0, s89
	s_mov_b64 exec, s[98:99]
	global_load_lds_dwordx4 v[106:107], off
	s_mov_b64 exec, -1
	s_waitcnt vmcnt(10)
	s_setprio 1
	s_barrier
	s_waitcnt lgkmcnt(0)
	v_mfma_f32_16x16x32_bf16 v[88:91], v[72:75], v[102:105], v[88:91]
	v_mfma_f32_16x16x32_bf16 v[84:87], v[80:83], v[102:105], v[84:87]
	v_mfma_f32_16x16x32_bf16 v[52:55], v[72:75], v[124:127], v[52:55]
	v_mfma_f32_16x16x32_bf16 v[48:51], v[80:83], v[124:127], v[48:51]
	v_mfma_f32_16x16x32_bf16 v[28:31], v[72:75], v[196:199], v[28:31]
	v_mfma_f32_16x16x32_bf16 v[24:27], v[80:83], v[196:199], v[24:27]
	v_mfma_f32_16x16x32_bf16 v[88:91], v[76:79], v[112:115], v[88:91]
	v_mfma_f32_16x16x32_bf16 v[84:87], v[98:101], v[112:115], v[84:87]
	v_mfma_f32_16x16x32_bf16 v[52:55], v[76:79], v[192:195], v[52:55]
	v_mfma_f32_16x16x32_bf16 v[48:51], v[98:101], v[192:195], v[48:51]
	v_mfma_f32_16x16x32_bf16 v[28:31], v[76:79], v[200:203], v[28:31]
	v_mfma_f32_16x16x32_bf16 v[24:27], v[98:101], v[200:203], v[24:27]
	s_barrier
	s_setprio 0
	v_add_u32_e32 v96, 0x10000, v225
	ds_read_b128 v[80:83], v96 offset:2048
	ds_read_b128 v[98:101], v96 offset:3072
	s_add_i32 s29, s46, s18
	v_lshl_add_u64 v[72:73], v[218:219], 0, s[6:7]
	s_mov_b32 m0, s29
	s_nop 0
	global_load_lds_dwordx4 v[72:73], off
	v_lshl_add_u64 v[72:73], v[220:221], 0, s[6:7]
	s_add_i32 m0, s29, 0x2000
	s_nop 0
	global_load_lds_dwordx4 v[72:73], off
	s_waitcnt vmcnt(6)
	s_setprio 1
	s_barrier
	v_mfma_f32_16x16x32_bf16 v[56:59], v[232:235], v[102:105], v[56:59]
	v_mfma_f32_16x16x32_bf16 v[76:79], v[236:239], v[112:115], v[56:59]
	v_mfma_f32_16x16x32_bf16 v[56:59], v[240:243], v[102:105], v[68:71]
	s_add_u32 s44, s44, 0x100
	v_mfma_f32_16x16x32_bf16 v[44:47], v[232:235], v[124:127], v[44:47]
	s_addc_u32 s45, s45, 0
	v_mfma_f32_16x16x32_bf16 v[40:43], v[240:243], v[124:127], v[40:43]
	s_add_u32 s87, s87, 0x100
	v_mfma_f32_16x16x32_bf16 v[20:23], v[232:235], v[196:199], v[20:23]
	s_addc_u32 vcc_lo, vcc_lo, 0
	v_mfma_f32_16x16x32_bf16 v[16:19], v[240:243], v[196:199], v[16:19]
	s_add_i32 s100, vcc_hi, 2
	s_cmp_ge_u32 s100, s37
	v_mfma_f32_16x16x32_bf16 v[72:75], v[244:247], v[112:115], v[56:59]
	s_mov_b32 s46, vcc_hi
	v_mfma_f32_16x16x32_bf16 v[44:47], v[236:239], v[192:195], v[44:47]
	v_mfma_f32_16x16x32_bf16 v[40:43], v[244:247], v[192:195], v[40:43]
	v_mfma_f32_16x16x32_bf16 v[20:23], v[236:239], v[200:203], v[20:23]
	v_mfma_f32_16x16x32_bf16 v[16:19], v[244:247], v[200:203], v[16:19]
	s_barrier
	s_setprio 0
	s_cbranch_scc0 .LBB0_1021
.Lrs_last:
	s_add_i32 vcc_hi, s46, 2
	s_add_u32 s84, s44, 0x80
	s_addc_u32 s47, s45, 0
	s_add_i32 s29, 0, 0x10000
	v_add_u32_e32 v96, s29, v225
	ds_read_b128 v[56:59], v96
	ds_read_b128 v[68:71], v96 offset:1024
	s_cmp_eq_u32 s90, s46
	s_cselect_b32 s46, s80, s84
	s_cselect_b32 s47, s81, s47
	s_cselect_b32 s85, s83, vcc_lo
	s_cselect_b32 s84, s82, s87
	s_add_i32 m0, s2, 0xc000
	ds_read_b128 v[102:105], v227
	ds_read_b128 v[112:115], v227 offset:1024
	ds_read_b128 v[124:127], v227 offset:2048
	ds_read_b128 v[192:195], v227 offset:3072
	ds_read_b128 v[196:199], v227 offset:4096
	ds_read_b128 v[200:203], v227 offset:5120
	global_load_lds_dwordx4 v188, s[44:45]
	s_add_i32 m0, s2, 0xe000
	s_mov_b64 exec, s[98:99]
	global_load_lds_dwordx4 v190, s[44:45]
	s_mov_b64 exec, -1
	s_cmp_eq_u32 s91, 1
	s_cbranch_scc0 .Lrs_nopre
	s_mov_b64 s[100:101], 0x8000
	v_lshl_add_u64 v[4:5], v[0:1], 0, s[100:101]
	v_lshl_add_u64 v[2:3], v[0:1], 0, s[12:13]
	global_load_dwordx4 v[140:143], v[0:1], off
	global_load_dwordx4 v[136:139], v[0:1], off offset:256
	global_load_dwordx4 v[108:111], v[4:5], off
	global_load_dwordx4 v[92:95], v[2:3], off offset:256
	s_mov_b64 s[100:101], 0x10000
	v_lshl_add_u64 v[2:3], v[0:1], 0, s[100:101]
	global_load_dwordx4 v[64:67], v[2:3], off
	global_load_dwordx4 v[60:63], v[2:3], off offset:256
	s_mov_b64 s[100:101], 0x30000
	v_lshl_add_u64 v[2:3], v[0:1], 0, s[100:101]
	global_load_dwordx4 v[36:39], v[2:3], off
	global_load_dwordx4 v[32:35], v[2:3], off offset:256
	s_mov_b64 s[100:101], 0x38000
	v_lshl_add_u64 v[2:3], v[0:1], 0, s[100:101]
	global_load_dwordx4 v[12:15], v[2:3], off
	global_load_dwordx4 v[8:11], v[2:3], off offset:256
	s_mov_b64 s[100:101], 0x40000
	v_lshl_add_u64 v[2:3], v[0:1], 0, s[100:101]
	global_load_dwordx4 v[4:7], v[2:3], off
	global_load_dwordx4 v[0:3], v[2:3], off offset:256
.Lrs_nopre:
	s_waitcnt lgkmcnt(6)
	s_setprio 1
	s_barrier
	s_waitcnt lgkmcnt(0)
	v_mfma_f32_16x16x32_bf16 v[172:175], v[56:59], v[102:105], v[172:175]
	v_mfma_f32_16x16x32_bf16 v[168:171], v[80:83], v[102:105], v[168:171]
	v_mfma_f32_16x16x32_bf16 v[156:159], v[56:59], v[124:127], v[156:159]
	v_mfma_f32_16x16x32_bf16 v[152:155], v[80:83], v[124:127], v[152:155]
	v_mfma_f32_16x16x32_bf16 v[132:135], v[56:59], v[196:199], v[132:135]
	v_mfma_f32_16x16x32_bf16 v[128:131], v[80:83], v[196:199], v[128:131]
	v_mfma_f32_16x16x32_bf16 v[172:175], v[68:71], v[112:115], v[172:175]
	v_mfma_f32_16x16x32_bf16 v[168:171], v[98:101], v[112:115], v[168:171]
	v_mfma_f32_16x16x32_bf16 v[156:159], v[68:71], v[192:195], v[156:159]
	v_mfma_f32_16x16x32_bf16 v[152:155], v[98:101], v[192:195], v[152:155]
	v_mfma_f32_16x16x32_bf16 v[132:135], v[68:71], v[200:203], v[132:135]
	v_mfma_f32_16x16x32_bf16 v[128:131], v[98:101], v[200:203], v[128:131]
	s_barrier
	s_setprio 0
	s_add_i32 s96, 0, 0x14000
	s_add_i32 s29, s29, s18
	v_add_u32_e32 v96, s96, v225
	v_lshl_add_u64 v[106:107], s[84:85], 0, v[182:183]
	s_mov_b32 m0, s29
	ds_read_b128 v[228:231], v96
	ds_read_b128 v[232:235], v96 offset:1024
	ds_read_b128 v[236:239], v96 offset:2048
	ds_read_b128 v[240:243], v96 offset:3072
	global_load_lds_dwordx4 v182, s[84:85]
	v_lshl_add_u64 v[248:249], s[84:85], 0, v[186:187]
	s_add_i32 m0, s29, 0x2000
	s_nop 0
	global_load_lds_dwordx4 v186, s[84:85]
	s_setprio 1
	s_barrier
	s_waitcnt lgkmcnt(0)
	v_mfma_f32_16x16x32_bf16 v[164:167], v[228:231], v[102:105], v[164:167]
	v_mfma_f32_16x16x32_bf16 v[102:105], v[236:239], v[102:105], v[160:163]
	v_mfma_f32_16x16x32_bf16 v[120:123], v[228:231], v[196:199], v[120:123]
	s_mov_b32 m0, s2
	v_mfma_f32_16x16x32_bf16 v[116:119], v[236:239], v[196:199], v[116:119]
	v_lshl_add_u64 v[250:251], s[46:47], 0, v[176:177]
	v_mfma_f32_16x16x32_bf16 v[164:167], v[232:235], v[112:115], v[164:167]
	v_mfma_f32_16x16x32_bf16 v[102:105], v[240:243], v[112:115], v[102:105]
	v_mfma_f32_16x16x32_bf16 v[112:115], v[228:231], v[124:127], v[148:151]
	v_mfma_f32_16x16x32_bf16 v[124:127], v[236:239], v[124:127], v[144:147]
	v_mfma_f32_16x16x32_bf16 v[120:123], v[232:235], v[200:203], v[120:123]
	v_mfma_f32_16x16x32_bf16 v[116:119], v[240:243], v[200:203], v[116:119]
	v_mfma_f32_16x16x32_bf16 v[112:115], v[232:235], v[192:195], v[112:115]
	v_mfma_f32_16x16x32_bf16 v[124:127], v[240:243], v[192:195], v[124:127]
	s_barrier
	s_setprio 0
	ds_read_b128 v[144:147], v227 offset:16384
	ds_read_b128 v[148:151], v227 offset:17408
	ds_read_b128 v[160:163], v227 offset:18432
	ds_read_b128 v[192:195], v227 offset:19456
	ds_read_b128 v[196:199], v227 offset:20480
	ds_read_b128 v[200:203], v227 offset:21504
	global_load_lds_dwordx4 v176, s[46:47]
	v_lshl_add_u64 v[252:253], s[46:47], 0, v[184:185]
	s_mov_b32 m0, s3
	s_mov_b64 exec, s[98:99]
	global_load_lds_dwordx4 v184, s[46:47]
	s_mov_b64 exec, -1
	s_waitcnt vmcnt(22)
	s_setprio 1
	s_barrier
	s_waitcnt lgkmcnt(0)
	v_mfma_f32_16x16x32_bf16 v[88:91], v[56:59], v[144:147], v[88:91]
	v_mfma_f32_16x16x32_bf16 v[84:87], v[80:83], v[144:147], v[84:87]
	v_mfma_f32_16x16x32_bf16 v[52:55], v[56:59], v[160:163], v[52:55]
	v_mfma_f32_16x16x32_bf16 v[48:51], v[80:83], v[160:163], v[48:51]
	v_mfma_f32_16x16x32_bf16 v[28:31], v[56:59], v[196:199], v[28:31]
	v_mfma_f32_16x16x32_bf16 v[24:27], v[80:83], v[196:199], v[24:27]
	v_mfma_f32_16x16x32_bf16 v[88:91], v[68:71], v[148:151], v[88:91]
	v_mfma_f32_16x16x32_bf16 v[84:87], v[98:101], v[148:151], v[84:87]
	v_mfma_f32_16x16x32_bf16 v[52:55], v[68:71], v[192:195], v[52:55]
	v_mfma_f32_16x16x32_bf16 v[48:51], v[98:101], v[192:195], v[48:51]
	v_mfma_f32_16x16x32_bf16 v[28:31], v[68:71], v[200:203], v[28:31]
	v_mfma_f32_16x16x32_bf16 v[24:27], v[98:101], v[200:203], v[24:27]
	s_barrier
	s_setprio 0
	v_add_u32_e32 v96, 0x18000, v225
	ds_read_b128 v[80:83], v96 offset:2048
	ds_read_b128 v[98:101], v96 offset:3072
	s_add_u32 s84, s84, s57
	s_addc_u32 s85, s85, 0
	s_add_i32 s29, s96, s18
	v_lshl_add_u64 v[218:219], s[84:85], 0, v[182:183]
	s_mov_b32 m0, s29
	v_lshl_add_u64 v[220:221], s[84:85], 0, v[186:187]
	global_load_lds_dwordx4 v182, s[84:85]
	s_add_i32 m0, s29, 0x2000
	s_nop 0
	global_load_lds_dwordx4 v186, s[84:85]
	s_waitcnt vmcnt(18)
	s_setprio 1
	s_barrier
	v_mfma_f32_16x16x32_bf16 v[44:47], v[228:231], v[160:163], v[44:47]
	v_mfma_f32_16x16x32_bf16 v[40:43], v[236:239], v[160:163], v[40:43]
	v_mfma_f32_16x16x32_bf16 v[20:23], v[228:231], v[196:199], v[20:23]
	s_add_i32 s29, 0, 0x18000
	v_mfma_f32_16x16x32_bf16 v[16:19], v[236:239], v[196:199], v[16:19]
	v_add_u32_e32 v96, s29, v225
	v_mfma_f32_16x16x32_bf16 v[56:59], v[228:231], v[144:147], v[76:79]
	v_mfma_f32_16x16x32_bf16 v[68:71], v[236:239], v[144:147], v[72:75]
	v_mfma_f32_16x16x32_bf16 v[44:47], v[232:235], v[192:195], v[44:47]
	v_mfma_f32_16x16x32_bf16 v[40:43], v[240:243], v[192:195], v[40:43]
	v_mfma_f32_16x16x32_bf16 v[20:23], v[232:235], v[200:203], v[20:23]
	v_mfma_f32_16x16x32_bf16 v[16:19], v[240:243], v[200:203], v[16:19]
	v_mfma_f32_16x16x32_bf16 v[56:59], v[232:235], v[148:151], v[56:59]
	v_mfma_f32_16x16x32_bf16 v[68:71], v[240:243], v[148:151], v[68:71]
	s_barrier
	s_setprio 0
	ds_read_b128 v[72:75], v96
	ds_read_b128 v[76:79], v96 offset:1024
	s_add_u32 s46, s46, s64
	s_addc_u32 s47, s47, 0
	s_mov_b32 m0, s4
	ds_read_b128 v[144:147], v227 offset:32768
	ds_read_b128 v[148:151], v227 offset:33792
	ds_read_b128 v[192:195], v227 offset:34816
	ds_read_b128 v[196:199], v227 offset:35840
	ds_read_b128 v[200:203], v227 offset:36864
	ds_read_b128 v[228:231], v227 offset:37888
	global_load_lds_dwordx4 v176, s[46:47]
	s_mov_b32 m0, s5
	s_mov_b64 exec, s[98:99]
	global_load_lds_dwordx4 v184, s[46:47]
	s_mov_b64 exec, -1
	s_waitcnt lgkmcnt(6)
	s_setprio 1
	s_barrier
	s_waitcnt lgkmcnt(0)
	v_mfma_f32_16x16x32_bf16 v[160:163], v[72:75], v[144:147], v[172:175]
	v_mfma_f32_16x16x32_bf16 v[172:175], v[76:79], v[148:151], v[160:163]
	v_mfma_f32_16x16x32_bf16 v[160:163], v[80:83], v[144:147], v[168:171]
	v_mfma_f32_16x16x32_bf16 v[156:159], v[72:75], v[192:195], v[156:159]
	v_mfma_f32_16x16x32_bf16 v[152:155], v[80:83], v[192:195], v[152:155]
	v_mfma_f32_16x16x32_bf16 v[132:135], v[72:75], v[200:203], v[132:135]
	v_mfma_f32_16x16x32_bf16 v[128:131], v[80:83], v[200:203], v[128:131]
	v_mfma_f32_16x16x32_bf16 v[168:171], v[98:101], v[148:151], v[160:163]
	v_mfma_f32_16x16x32_bf16 v[156:159], v[76:79], v[196:199], v[156:159]
	v_mfma_f32_16x16x32_bf16 v[152:155], v[98:101], v[196:199], v[152:155]
	v_mfma_f32_16x16x32_bf16 v[132:135], v[76:79], v[228:231], v[132:135]
	v_mfma_f32_16x16x32_bf16 v[128:131], v[98:101], v[228:231], v[128:131]
	s_barrier
	s_setprio 0
	s_add_i32 s46, 0, 0x1c000
	s_add_i32 s29, s29, s18
	v_add_u32_e32 v96, s46, v225
	v_lshl_add_u64 v[106:107], v[106:107], 0, s[6:7]
	s_mov_b32 m0, s29
	ds_read_b128 v[232:235], v96
	ds_read_b128 v[236:239], v96 offset:1024
	ds_read_b128 v[240:243], v96 offset:2048
	ds_read_b128 v[244:247], v96 offset:3072
	global_load_lds_dwordx4 v[106:107], off
	v_lshl_add_u64 v[106:107], v[248:249], 0, s[6:7]
	s_add_i32 m0, s29, 0x2000
	s_nop 0
	global_load_lds_dwordx4 v[106:107], off
	s_setprio 1
	s_barrier
	s_waitcnt lgkmcnt(0)
	v_mfma_f32_16x16x32_bf16 v[160:163], v[232:235], v[144:147], v[164:167]
	v_mfma_f32_16x16x32_bf16 v[102:105], v[240:243], v[144:147], v[102:105]
	v_mfma_f32_16x16x32_bf16 v[164:167], v[236:239], v[148:151], v[160:163]
	s_mov_b32 m0, s88
	v_mfma_f32_16x16x32_bf16 v[160:163], v[244:247], v[148:151], v[102:105]
	v_lshl_add_u64 v[106:107], v[250:251], 0, s[6:7]
	v_mfma_f32_16x16x32_bf16 v[102:105], v[232:235], v[192:195], v[112:115]
	v_mfma_f32_16x16x32_bf16 v[148:151], v[236:239], v[196:199], v[102:105]
	v_mfma_f32_16x16x32_bf16 v[102:105], v[240:243], v[192:195], v[124:127]
	v_mfma_f32_16x16x32_bf16 v[144:147], v[244:247], v[196:199], v[102:105]
	v_mfma_f32_16x16x32_bf16 v[102:105], v[232:235], v[200:203], v[120:123]
	v_mfma_f32_16x16x32_bf16 v[120:123], v[236:239], v[228:231], v[102:105]
	v_mfma_f32_16x16x32_bf16 v[102:105], v[240:243], v[200:203], v[116:119]
	v_mfma_f32_16x16x32_bf16 v[116:119], v[244:247], v[228:231], v[102:105]
	s_barrier
	s_setprio 0
	s_nop 2
	ds_read_b128 v[102:105], v227 offset:49152
	ds_read_b128 v[112:115], v227 offset:50176
	ds_read_b128 v[124:127], v227 offset:51200
	ds_read_b128 v[192:195], v227 offset:52224
	ds_read_b128 v[196:199], v227 offset:53248
	ds_read_b128 v[200:203], v227 offset:54272
	global_load_lds_dwordx4 v[106:107], off
	v_lshl_add_u64 v[106:107], v[252:253], 0, s[6:7]
	s_mov_b32 m0, s89
	s_mov_b64 exec, s[98:99]
	global_load_lds_dwordx4 v[106:107], off
	s_mov_b64 exec, -1
	s_cmp_lg_u64 s[42:43], 0
	s_cbranch_scc1 .Lrs_l7
	s_waitcnt vmcnt(10)
.Lrs_l7:
	s_setprio 1
	s_barrier
	s_waitcnt lgkmcnt(0)
	v_mfma_f32_16x16x32_bf16 v[88:91], v[72:75], v[102:105], v[88:91]
	v_mfma_f32_16x16x32_bf16 v[84:87], v[80:83], v[102:105], v[84:87]
	v_mfma_f32_16x16x32_bf16 v[52:55], v[72:75], v[124:127], v[52:55]
	v_mfma_f32_16x16x32_bf16 v[48:51], v[80:83], v[124:127], v[48:51]
	v_mfma_f32_16x16x32_bf16 v[28:31], v[72:75], v[196:199], v[28:31]
	v_mfma_f32_16x16x32_bf16 v[24:27], v[80:83], v[196:199], v[24:27]
	v_mfma_f32_16x16x32_bf16 v[88:91], v[76:79], v[112:115], v[88:91]
	v_mfma_f32_16x16x32_bf16 v[84:87], v[98:101], v[112:115], v[84:87]
	v_mfma_f32_16x16x32_bf16 v[52:55], v[76:79], v[192:195], v[52:55]
	v_mfma_f32_16x16x32_bf16 v[48:51], v[98:101], v[192:195], v[48:51]
	v_mfma_f32_16x16x32_bf16 v[28:31], v[76:79], v[200:203], v[28:31]
	v_mfma_f32_16x16x32_bf16 v[24:27], v[98:101], v[200:203], v[24:27]
	s_barrier
	s_setprio 0
	v_add_u32_e32 v96, 0x10000, v225
	ds_read_b128 v[80:83], v96 offset:2048
	ds_read_b128 v[98:101], v96 offset:3072
	s_add_i32 s29, s46, s18
	v_lshl_add_u64 v[72:73], v[218:219], 0, s[6:7]
	s_mov_b32 m0, s29
	s_nop 0
	global_load_lds_dwordx4 v[72:73], off
	v_lshl_add_u64 v[72:73], v[220:221], 0, s[6:7]
	s_add_i32 m0, s29, 0x2000
	s_nop 0
	global_load_lds_dwordx4 v[72:73], off
	s_cmp_lg_u64 s[42:43], 0
	s_cbranch_scc1 .Lrs_l8
	s_waitcnt vmcnt(6)
.Lrs_l8:
	s_setprio 1
	s_barrier
	v_mfma_f32_16x16x32_bf16 v[56:59], v[232:235], v[102:105], v[56:59]
	v_mfma_f32_16x16x32_bf16 v[76:79], v[236:239], v[112:115], v[56:59]
	v_mfma_f32_16x16x32_bf16 v[56:59], v[240:243], v[102:105], v[68:71]
	s_add_u32 s44, s44, 0x100
	v_mfma_f32_16x16x32_bf16 v[44:47], v[232:235], v[124:127], v[44:47]
	s_addc_u32 s45, s45, 0
	v_mfma_f32_16x16x32_bf16 v[40:43], v[240:243], v[124:127], v[40:43]
	s_add_u32 s87, s87, 0x100
	v_mfma_f32_16x16x32_bf16 v[20:23], v[232:235], v[196:199], v[20:23]
	s_addc_u32 vcc_lo, vcc_lo, 0
	v_mfma_f32_16x16x32_bf16 v[16:19], v[240:243], v[196:199], v[16:19]
	s_cmp_ge_u32 vcc_hi, s37
	v_mfma_f32_16x16x32_bf16 v[72:75], v[244:247], v[112:115], v[56:59]
	s_mov_b32 s46, vcc_hi
	v_mfma_f32_16x16x32_bf16 v[44:47], v[236:239], v[192:195], v[44:47]
	v_mfma_f32_16x16x32_bf16 v[40:43], v[244:247], v[192:195], v[40:43]
	v_mfma_f32_16x16x32_bf16 v[20:23], v[236:239], v[200:203], v[20:23]
	v_mfma_f32_16x16x32_bf16 v[16:19], v[244:247], v[200:203], v[16:19]
	s_barrier
	s_setprio 0
	s_waitcnt vmcnt(0)
	s_waitcnt lgkmcnt(0)
	s_mul_i32 s44, s86, 0xc0
	s_add_i32 s44, s44, s19
	s_cmpk_lt_u32 s44, 0x2000
	v_or_b32_e32 v198, s44, v223
	s_cselect_b32 s44, 1, 2
	v_mov_b32_e32 v56, s44
	v_cmp_lt_i32_e32 vcc, s23, v198
	v_lshl_or_b32 v192, s72, 8, v226
	v_ashrrev_i32_e32 v193, 31, v192
	v_cndmask_b32_e32 v228, 0, v56, vcc
	v_mul_u32_u24_e32 v56, 0x1800, v228
	v_lshlrev_b32_e32 v96, 2, v56
	v_lshl_add_u64 v[56:57], s[70:71], 0, v[96:97]
	v_lshlrev_b64 v[68:69], 2, v[192:193]
	v_lshl_add_u64 v[124:125], v[56:57], 0, v[68:69]
	global_load_dwordx4 v[56:59], v[124:125], off
	v_cndmask_b32_e64 v70, 0, 1, s[78:79]
	v_cmp_ne_u32_e64 s[46:47], 1, v70
	s_andn2_b64 vcc, exec, s[78:79]
	v_lshl_add_u64 v[196:197], s[54:55], 0, v[68:69]
	s_cbranch_vccnz .LBB0_1024
	global_load_dwordx4 v[80:83], v[196:197], off
	s_waitcnt vmcnt(0)
	v_pk_mul_f32 v[58:59], v[58:59], v[82:83]
	v_pk_mul_f32 v[56:57], v[56:57], v[80:81]
